# pass1: next unit's chunk loads issued in the middle of the current unit's MFMA part into their own registers, loop top waits vmcnt(16) so the state stores stay in flight (on top of pass2 hoist + gain
# speedup vs baseline: 1.0173x; 1.0031x over previous
; __device__ __forceinline__ void hgrn_ld_chunks(const bf16* base, int tid, v4u (&w)[4]) {
; #pragma unroll
;     for (int m = 0; m < 4; ++m) { const int cid = tid + 512 * m; w[m] = *(const v4u*)(base + (size_t)(cid >> 4) * EIN + 8 * (cid & 15)); }
; }
; __device__ __forceinline__ void hgrn_pass1(const bf16* PROJ, bf16* ST, float* DEC, const float* lbl, int e, int L, LAS unsigned char* lds) {
;     ...
;     for (int u = blockIdx.x; u < nunits; u += gridDim.x) {
;         const int h = u & 3, sgi = u >> 2, seq = sgi / nseg, seg = sgi % nseg;
;         const bf16* pb = PROJ + ((size_t)seq * L + (size_t)seg * HG) * EIN + 128 * h;
;         v4u cv[4], cz[2][4];
;         hgrn_ld_chunks(pb + 1536, tid, cv); hgrn_ld_chunks(pb + 512, tid, cz[0]); hgrn_ld_chunks(pb + 1024, tid, cz[1]);
.LBB0_425:
	s_and_b64 s[0:1], s[70:71], exec
	s_cselect_b32 s0, s4, s39
	s_cmp_lg_u32 s0, 0
	s_cselect_b64 s[0:1], -1, 0
	s_and_b64 s[2:3], s[0:1], exec
	s_cselect_b32 s3, s38, 0x4000
	v_mov_b32_e32 v64, v187
	s_lshr_b32 s5, s3, 4
	s_cmp_ge_i32 s84, s5
	v_readfirstlane_b32 s2, v64
	s_cbranch_scc1 .LBB0_424
	s_and_b64 s[10:11], s[70:71], s[0:1]
	s_and_b64 s[6:7], s[10:11], exec
	s_cselect_b32 s6, 0x10000000, 0
	s_add_u32 s6, s78, s6
	s_addc_u32 s7, s79, 0
	s_lshr_b32 s8, s3, 7
	v_ashrrev_i32_e32 v2, 4, v64
	s_and_b64 s[10:11], s[10:11], exec
	v_ashrrev_i32_e32 v3, 31, v2
	s_cselect_b32 s3, 0x100000, 0
	v_lshlrev_b64 v[66:67], 13, v[2:3]
	v_add_u32_e32 v3, 0x200, v64
	s_add_u32 s10, s19, s3
	v_ashrrev_i32_e32 v4, 4, v3
	v_add_u32_e32 v3, 0x400, v64
	s_addc_u32 s11, s77, 0
	v_ashrrev_i32_e32 v6, 4, v3
	v_add_u32_e32 v3, 0x600, v64
	s_and_b64 s[12:13], s[0:1], exec
	v_ashrrev_i32_e32 v8, 4, v3
	v_lshlrev_b32_e32 v3, 4, v64
	s_waitcnt lgkmcnt(0)
	v_ashrrev_i32_e32 v1, 7, v64
	v_readlane_b32 s40, v248, 58
	v_and_b32_e32 v10, 0x7f, v64
	v_ashrrev_i32_e32 v5, 31, v4
	v_ashrrev_i32_e32 v7, 31, v6
	v_and_b32_e32 v3, 0xf0, v3
	v_readlane_b32 s9, v248, 49
	s_movk_i32 s13, 0x2200
	s_cselect_b32 s3, 0x8000000, 0
	v_readlane_b32 s54, v247, 8
	v_lshlrev_b64 v[68:69], 13, v[4:5]
	v_lshlrev_b64 v[70:71], 13, v[6:7]
	v_add_u32_e32 v5, s9, v3
	v_mul_lo_u32 v7, v2, s30
	v_lshlrev_b32_e32 v2, 1, v10
	v_mul_lo_u32 v3, v1, s13
	v_readlane_b32 s55, v247, 9
	s_add_u32 s3, s54, s3
	v_add3_u32 v78, s9, v2, v3
	v_readlane_b32 s9, v248, 50
	s_addc_u32 s12, s55, 0
	v_lshl_add_u64 v[74:75], v[64:65], 2, s[10:11]
	v_lshl_add_u32 v79, v10, 2, s9
	s_ashr_i32 s9, s2, 8
	s_lshr_b32 s2, s2, 1
	v_and_b32_e32 v13, 31, v64
	s_mul_i32 s10, s9, 0x8800
	s_and_b32 s2, s2, 0x60
	s_add_i32 s10, s10, 0
	v_or_b32_e32 v3, s2, v13
	s_lshl_b32 s2, s2, 1
	s_add_u32 s2, s3, s2
	v_bfe_u32 v2, v64, 5, 1
	s_addc_u32 s3, s12, 0
	v_lshlrev_b32_e32 v0, 3, v64
	v_cmp_gt_u32_e32 vcc, s96, v64
	v_mov_b32_e32 v14, s10
	v_lshlrev_b32_e32 v64, 3, v2
	s_and_b64 s[0:1], s[0:1], exec
	v_mad_u32_u24 v14, v3, s30, v14
	v_lshlrev_b32_e32 v15, 4, v2
	v_lshl_add_u64 v[2:3], s[2:3], 0, v[64:65]
	s_cselect_b32 s10, 26, 27
	v_lshlrev_b32_e32 v64, 8, v13
	s_abs_i32 s12, s8
	v_lshl_add_u64 v[76:77], v[2:3], 0, v[64:65]
	v_cvt_f32_u32_e32 v2, s12
	s_sub_i32 s0, 0, s12
	v_ashrrev_i32_e32 v9, 31, v8
	v_readlane_b32 s13, v248, 48
	v_rcp_iflag_f32_e32 v2, v2
	v_readlane_b32 s42, v248, 60
	v_readlane_b32 s43, v248, 61
	v_readlane_b32 s44, v248, 62
	v_mul_f32_e32 v2, 0x4f7ffffe, v2
	v_cvt_u32_f32_e32 v2, v2
	v_readlane_b32 s45, v248, 63
	v_readlane_b32 s46, v247, 0
	v_readlane_b32 s47, v247, 1
	v_readfirstlane_b32 s1, v2
	s_mul_i32 s0, s0, s1
	v_readlane_b32 s48, v247, 2
	v_readlane_b32 s49, v247, 3
	v_readlane_b32 s50, v247, 4
	v_readlane_b32 s51, v247, 5
	v_readlane_b32 s52, v247, 6
	v_readlane_b32 s53, v247, 7
	v_lshlrev_b64 v[72:73], 13, v[8:9]
	v_mov_b32_e32 v9, s13
	v_or_b32_e32 v80, 32, v15
	v_or_b32_e32 v82, 64, v15
	v_or_b32_e32 v83, 0x60, v15
	v_or_b32_e32 v84, 0x80, v15
	v_or_b32_e32 v85, 0xa0, v15
	v_or_b32_e32 v86, 0xc0, v15
	v_or_b32_e32 v87, 0xe0, v15
	s_mul_hi_u32 s0, s1, s0
	v_and_b32_e32 v0, 0x78, v0
	v_mul_lo_u32 v4, v4, s30
	v_mul_lo_u32 v6, v6, s30
	v_mul_lo_u32 v8, v8, s30
	v_mad_u32_u24 v11, v10, s30, v9
	v_lshlrev_b32_e32 v12, 6, v1
	v_mad_u32_u24 v10, v10, s30, 0
	v_lshlrev_b32_e32 v16, 9, v1
	v_cmp_gt_i32_e64 s[42:43], 0, v1
	v_cmp_gt_i32_e64 s[44:45], 1, v1
	v_cmp_gt_i32_e64 s[46:47], 2, v1
	v_cmp_gt_i32_e64 s[48:49], 3, v1
	v_cmp_lt_i32_e64 s[50:51], 0, v1
	v_cmp_lt_i32_e64 s[52:53], 1, v1
	v_cmp_lt_i32_e64 s[54:55], 2, v1
	v_cmp_lt_i32_e64 s[56:57], 3, v1
	v_mul_u32_u24_e32 v1, 0x110, v13
	v_add_u32_e32 v17, s13, v15
	v_add_u32_e32 v18, s13, v80
	v_mad_u32_u24 v81, v13, s30, v9
	v_add_u32_e32 v9, s13, v82
	v_add_u32_e32 v19, s13, v83
	v_add_u32_e32 v20, s13, v84
	v_add_u32_e32 v21, s13, v85
	v_add_u32_e32 v22, s13, v86
	v_add_u32_e32 v23, s13, v87
	s_add_i32 s13, s1, s0
	v_readlane_b32 s0, v248, 34
	s_ashr_i32 s11, s8, 31
	v_lshlrev_b32_e32 v64, 1, v0
	v_add_u32_e32 v88, v11, v12
	v_add_u32_e32 v89, v14, v15
	v_add_u32_e32 v90, v17, v1
	v_add_u32_e32 v91, v18, v1
	v_add_u32_e32 v92, v9, v1
	v_add_u32_e32 v93, v19, v1
	v_add_u32_e32 v94, v20, v1
	v_add_u32_e32 v95, v21, v1
	v_add_u32_e32 v96, v22, v1
	v_add_u32_e32 v97, v23, v1
	v_add_u32_e32 v98, v5, v7
	v_add_u32_e32 v99, v5, v4
	v_add_u32_e32 v100, v5, v6
	v_add_u32_e32 v101, v5, v8
	v_add_u32_e32 v102, v79, v16
	v_add_u32_e32 v103, v10, v12
	v_readlane_b32 s14, v248, 35
	s_mov_b32 s2, s0
	s_mov_b32 s15, s84
	v_readlane_b32 s41, v248, 59
	s_ashr_i32 s101, s15, 2
	s_abs_i32 s3, s101
	s_mul_hi_u32 s16, s3, s13
	s_mul_i32 s17, s16, s12
	s_ashr_i32 s100, s15, 31
	s_sub_i32 s3, s3, s17
	s_xor_b32 s100, s100, s11
	s_add_i32 s17, s16, 1
	s_sub_i32 s18, s3, s12
	s_cmp_ge_u32 s3, s12
	s_cselect_b32 s16, s17, s16
	s_cselect_b32 s3, s18, s3
	s_add_i32 s17, s16, 1
	s_cmp_ge_u32 s3, s12
	s_cselect_b32 s3, s17, s16
	s_xor_b32 s3, s3, s100
	s_sub_i32 s100, s3, s100
	s_mul_i32 s3, s100, s8
	s_sub_i32 s16, s101, s3
	s_ashr_i32 s17, s16, 31
	s_ashr_i32 s101, s100, 31
	s_lshl_b64 s[16:17], s[16:17], 20
	s_add_u32 s3, s6, s16
	s_addc_u32 s16, s7, s17
	s_lshl_b64 s[100:101], s[100:101], s10
	s_add_u32 s100, s3, s100
	s_addc_u32 s101, s16, s101
	s_and_b32 s3, s14, 0x180
	s_lshl_b32 s3, s3, 1
	s_add_u32 s100, s100, s3
	s_addc_u32 s101, s101, 0
	v_lshl_add_u64 v[136:137], s[100:101], 0, v[64:65]
	v_lshl_add_u64 v[138:139], v[136:137], 0, v[66:67]
	global_load_dwordx4 v[152:155], v[138:139], off offset:3072
	v_lshl_add_u64 v[140:141], v[136:137], 0, v[68:69]
	global_load_dwordx4 v[156:159], v[140:141], off offset:3072
	v_lshl_add_u64 v[144:145], v[136:137], 0, v[70:71]
	global_load_dwordx4 v[160:163], v[144:145], off offset:3072
	v_lshl_add_u64 v[148:149], v[136:137], 0, v[72:73]
	global_load_dwordx4 v[164:167], v[148:149], off offset:3072
	global_load_dwordx4 v[168:171], v[140:141], off offset:1024
	global_load_dwordx4 v[172:175], v[148:149], off offset:1024
	global_load_dwordx4 v[176:179], v[138:139], off offset:1024
	s_nop 0
	global_load_dwordx4 v[136:139], v[138:139], off offset:2048
	s_nop 0
	global_load_dwordx4 v[140:143], v[140:141], off offset:2048
	s_nop 0
	global_load_dwordx4 v[180:183], v[144:145], off offset:1024
	s_nop 0
	global_load_dwordx4 v[144:147], v[144:145], off offset:2048
	s_nop 0
	global_load_dwordx4 v[148:151], v[148:149], off offset:2048
	s_waitcnt vmcnt(0)
	s_branch .Lp1_body
; #define LAS __attribute__((address_space(3)))
; __device__ __forceinline__ unsigned pk2(float lo, float hi) { const f32x2_t v = {lo, hi}; return __builtin_bit_cast(unsigned, __builtin_convertvector(v, bf16x2_t)); }
; __device__ __forceinline__ float ex2(float x) { return __builtin_amdgcn_exp2f(x); }
; __device__ __forceinline__ void hgrn_pass1(const bf16* PROJ, bf16* ST, float* DEC, const float* lbl, int e, int L, LAS unsigned char* lds) {
;     ...
;             float off = 0.f, dtot = 0.f;
; #pragma unroll
;             for (int q = 0; q < 4; ++q) { const float tv = TOT[(dir * 4 + q) * 128 + i]; dtot += tv; if (dir == 0 ? (q > tq) : (q < tq)) off += tv; }
;             if (tq == 0) DEC[(size_t)(u * 2 + dir) * 128 + i] = ex2(dtot);
;             if (dir == 0) { float run = off;
; #pragma unroll
;     ...
;             else { float run = off;
; #pragma unroll
;                 for (int uu = 0; uu < 32; ++uu) { kk[uu] *= ex2(run); run += lf[uu]; } }
;             LAS unsigned char* KT = lds + dir * IMG;
; #pragma unroll
;             for (int m = 0; m < 4; ++m) { v4u w;
; #pragma unroll
;                 for (int x = 0; x < 4; ++x) w[x] = pk2(kk[8 * m + 2 * x], kk[8 * m + 2 * x + 1]);
;                 *(LAS v4u*)(KT + i * LSTR + (32 * tq + 8 * m) * 2) = w; }
.LBB0_427:
	s_or_b64 exec, exec, s[0:1]
	v_cndmask_b32_e64 v0, 0, v0, s[50:51]
	v_add_f32_e32 v1, v1, v0
	v_cndmask_b32_e64 v0, v0, v1, s[52:53]
	s_waitcnt lgkmcnt(0)
	v_add_f32_e32 v1, v2, v0
	v_cndmask_b32_e64 v0, v0, v1, s[54:55]
	v_add_f32_e32 v1, v3, v0
	v_cndmask_b32_e64 v0, v0, v1, s[56:57]
	v_add_f32_e32 v3, v0, v4
	v_exp_f32_e32 v36, v4
	v_add_f32_e32 v4, v3, v5
	v_exp_f32_e32 v37, v5
	v_add_f32_e32 v5, v4, v6
	v_exp_f32_e32 v38, v6
	v_add_f32_e32 v6, v5, v7
	v_exp_f32_e32 v39, v7
	v_add_f32_e32 v7, v6, v8
	v_exp_f32_e32 v40, v8
	v_add_f32_e32 v8, v7, v9
	v_exp_f32_e32 v41, v9
	v_add_f32_e32 v9, v8, v10
	v_exp_f32_e32 v42, v10
	v_add_f32_e32 v10, v9, v11
	v_exp_f32_e32 v43, v11
	v_add_f32_e32 v11, v10, v12
	v_exp_f32_e32 v44, v12
	v_add_f32_e32 v12, v11, v13
	v_exp_f32_e32 v45, v13
	v_add_f32_e32 v13, v12, v14
	v_exp_f32_e32 v46, v14
	v_add_f32_e32 v14, v13, v15
	v_exp_f32_e32 v47, v15
	v_add_f32_e32 v15, v14, v16
	v_exp_f32_e32 v48, v16
	v_add_f32_e32 v16, v15, v17
	v_exp_f32_e32 v49, v17
	v_add_f32_e32 v17, v16, v18
	v_exp_f32_e32 v50, v18
	v_add_f32_e32 v18, v17, v19
	v_exp_f32_e32 v51, v19
	v_add_f32_e32 v19, v18, v20
	v_exp_f32_e32 v52, v20
	v_add_f32_e32 v20, v19, v21
	v_exp_f32_e32 v53, v21
	v_add_f32_e32 v21, v20, v22
	v_exp_f32_e32 v54, v22
	v_add_f32_e32 v22, v21, v23
	v_exp_f32_e32 v55, v23
	v_add_f32_e32 v23, v22, v24
	v_exp_f32_e32 v56, v24
	v_add_f32_e32 v24, v23, v25
	v_exp_f32_e32 v57, v25
	v_add_f32_e32 v25, v24, v26
	v_exp_f32_e32 v58, v26
	v_add_f32_e32 v26, v25, v27
	v_exp_f32_e32 v59, v27
	v_add_f32_e32 v27, v26, v28
	v_exp_f32_e32 v60, v28
	v_add_f32_e32 v28, v27, v29
	v_exp_f32_e32 v61, v29
	v_add_f32_e32 v29, v28, v30
	v_exp_f32_e32 v62, v30
	v_add_f32_e32 v30, v29, v31
	v_exp_f32_e32 v63, v31
	v_add_f32_e32 v31, v30, v32
	v_exp_f32_e32 v104, v32
	v_add_f32_e32 v32, v31, v33
	v_exp_f32_e32 v106, v34
	v_exp_f32_e32 v107, v35
	v_add_f32_e32 v1, v32, v34
	v_exp_f32_e32 v2, v0
	v_exp_f32_e32 v3, v3
	v_exp_f32_e32 v4, v4
	v_exp_f32_e32 v5, v5
	v_exp_f32_e32 v6, v6
	v_exp_f32_e32 v7, v7
	v_exp_f32_e32 v8, v8
	v_exp_f32_e32 v9, v9
	v_exp_f32_e32 v1, v1
	v_exp_f32_e32 v10, v10
	v_exp_f32_e32 v11, v11
	v_exp_f32_e32 v12, v12
	v_exp_f32_e32 v13, v13
	v_exp_f32_e32 v14, v14
	v_exp_f32_e32 v15, v15
	v_exp_f32_e32 v16, v16
	v_exp_f32_e32 v17, v17
	v_exp_f32_e32 v0, v32
	v_exp_f32_e32 v105, v33
	v_exp_f32_e32 v18, v18
	v_exp_f32_e32 v19, v19
	v_exp_f32_e32 v20, v20
	v_exp_f32_e32 v21, v21
	v_exp_f32_e32 v22, v22
	v_exp_f32_e32 v23, v23
	v_exp_f32_e32 v24, v24
	v_exp_f32_e32 v25, v25
	v_pk_add_f32 v[36:37], v[36:37], 1.0 op_sel_hi:[1,0] neg_lo:[1,0] neg_hi:[1,0]
	v_pk_add_f32 v[38:39], v[38:39], 1.0 op_sel_hi:[1,0] neg_lo:[1,0] neg_hi:[1,0]
	v_pk_add_f32 v[40:41], v[40:41], 1.0 op_sel_hi:[1,0] neg_lo:[1,0] neg_hi:[1,0]
	v_pk_add_f32 v[42:43], v[42:43], 1.0 op_sel_hi:[1,0] neg_lo:[1,0] neg_hi:[1,0]
	v_exp_f32_e32 v26, v26
	v_exp_f32_e32 v27, v27
	v_exp_f32_e32 v28, v28
	v_exp_f32_e32 v29, v29
	v_exp_f32_e32 v30, v30
	v_exp_f32_e32 v31, v31
	v_pk_add_f32 v[44:45], v[44:45], 1.0 op_sel_hi:[1,0] neg_lo:[1,0] neg_hi:[1,0]
	v_pk_add_f32 v[46:47], v[46:47], 1.0 op_sel_hi:[1,0] neg_lo:[1,0] neg_hi:[1,0]
	v_pk_add_f32 v[48:49], v[48:49], 1.0 op_sel_hi:[1,0] neg_lo:[1,0] neg_hi:[1,0]
	v_pk_add_f32 v[50:51], v[50:51], 1.0 op_sel_hi:[1,0] neg_lo:[1,0] neg_hi:[1,0]
	v_pk_add_f32 v[106:107], v[106:107], 1.0 op_sel_hi:[1,0] neg_lo:[1,0] neg_hi:[1,0]
	v_pk_mul_f32 v[2:3], v[36:37], v[2:3]
	v_pk_mul_f32 v[4:5], v[38:39], v[4:5]
	v_pk_mul_f32 v[6:7], v[40:41], v[6:7]
	v_pk_mul_f32 v[8:9], v[42:43], v[8:9]
	v_pk_add_f32 v[52:53], v[52:53], 1.0 op_sel_hi:[1,0] neg_lo:[1,0] neg_hi:[1,0]
	v_pk_add_f32 v[54:55], v[54:55], 1.0 op_sel_hi:[1,0] neg_lo:[1,0] neg_hi:[1,0]
	v_pk_add_f32 v[56:57], v[56:57], 1.0 op_sel_hi:[1,0] neg_lo:[1,0] neg_hi:[1,0]
	v_pk_add_f32 v[58:59], v[58:59], 1.0 op_sel_hi:[1,0] neg_lo:[1,0] neg_hi:[1,0]
	v_pk_mul_f32 v[10:11], v[44:45], v[10:11]
	v_pk_mul_f32 v[12:13], v[46:47], v[12:13]
	v_pk_mul_f32 v[14:15], v[48:49], v[14:15]
	v_pk_mul_f32 v[16:17], v[50:51], v[16:17]
	v_pk_mul_f32 v[32:33], v[106:107], v[0:1]
	v_cvt_pk_bf16_f32 v0, v2, v3
	v_cvt_pk_bf16_f32 v1, v4, v5
	v_cvt_pk_bf16_f32 v2, v6, v7
	v_cvt_pk_bf16_f32 v3, v8, v9
	v_pk_add_f32 v[60:61], v[60:61], 1.0 op_sel_hi:[1,0] neg_lo:[1,0] neg_hi:[1,0]
	v_pk_add_f32 v[62:63], v[62:63], 1.0 op_sel_hi:[1,0] neg_lo:[1,0] neg_hi:[1,0]
	v_pk_add_f32 v[104:105], v[104:105], 1.0 op_sel_hi:[1,0] neg_lo:[1,0] neg_hi:[1,0]
	v_pk_mul_f32 v[18:19], v[52:53], v[18:19]
	v_pk_mul_f32 v[20:21], v[54:55], v[20:21]
	v_pk_mul_f32 v[22:23], v[56:57], v[22:23]
	v_pk_mul_f32 v[24:25], v[58:59], v[24:25]
	ds_write_b128 v103, v[0:3] offset:34816
	v_cvt_pk_bf16_f32 v0, v10, v11
	v_cvt_pk_bf16_f32 v1, v12, v13
	v_cvt_pk_bf16_f32 v2, v14, v15
	v_cvt_pk_bf16_f32 v3, v16, v17
	v_pk_mul_f32 v[26:27], v[60:61], v[26:27]
	v_pk_mul_f32 v[28:29], v[62:63], v[28:29]
	v_pk_mul_f32 v[30:31], v[104:105], v[30:31]
	ds_write_b128 v103, v[0:3] offset:34832
	v_cvt_pk_bf16_f32 v0, v18, v19
	v_cvt_pk_bf16_f32 v1, v20, v21
	v_cvt_pk_bf16_f32 v2, v22, v23
	v_cvt_pk_bf16_f32 v3, v24, v25
	ds_write_b128 v103, v[0:3] offset:34848
	v_cvt_pk_bf16_f32 v0, v26, v27
	v_cvt_pk_bf16_f32 v1, v28, v29
	v_cvt_pk_bf16_f32 v2, v30, v31
	v_cvt_pk_bf16_f32 v3, v32, v33
	ds_write_b128 v103, v[0:3] offset:34864
	s_waitcnt lgkmcnt(0)
	s_barrier
; #define LAS __attribute__((address_space(3)))
; __device__ __forceinline__ void hgrn_pass1(const bf16* PROJ, bf16* ST, float* DEC, const float* lbl, int e, int L, LAS unsigned char* lds) {
;     ...
;     for (int u = blockIdx.x; u < nunits; u += gridDim.x) {
;         const int h = u & 3, sgi = u >> 2, seq = sgi / nseg, seg = sgi % nseg;
;         const bf16* pb = PROJ + ((size_t)seq * L + (size_t)seg * HG) * EIN + 128 * h;
;         v4u cv[4], cz[2][4];
;         hgrn_ld_chunks(pb + 1536, tid, cv); hgrn_ld_chunks(pb + 512, tid, cz[0]); hgrn_ld_chunks(pb + 1024, tid, cz[1]);
;     ...
;         __syncthreads();
;         {
;             const int dir = wave >> 2, it = wave & 3, r32 = lane & 31, hh = lane >> 5;
;             const LAS unsigned char* KT = lds + dir * IMG;
;             f32x16 acc[4];
; #pragma unroll
;             for (int jt = 0; jt < 4; ++jt)
; #pragma unroll
;                 for (int x = 0; x < 16; ++x) acc[jt][x] = 0.f;
; #pragma unroll
;             for (int ks = 0; ks < 8; ++ks) {
;                 const bf16x8 a = *(const LAS bf16x8*)(KT + (32 * it + r32) * LSTR + (16 * ks + 8 * hh) * 2);
; #pragma unroll
;                 for (int jt = 0; jt < 4; ++jt) { const bf16x8 b = *(const LAS bf16x8*)(VT + (32 * jt + r32) * LSTR + (16 * ks + 8 * hh) * 2);
;                     acc[jt] = __builtin_amdgcn_mfma_f32_32x32x16_bf16(a, b, acc[jt], 0, 0, 0); }
;             }
	ds_read_b128 v[0:3], v90
	ds_read_b128 v[4:7], v89
	ds_read_b128 v[104:107], v89 offset:32
	s_waitcnt lgkmcnt(1)
	v_mfma_f32_32x32x16_bf16 v[48:63], v[4:7], v[0:3], 0
	v_add_u32_e32 v108, v81, v80
	ds_read_b128 v[0:3], v90 offset:8704
	ds_read_b128 v[108:111], v108
	s_add_i32 s0, s9, s2
	s_ashr_i32 s1, s0, 31
	s_lshl_b64 s[0:1], s[0:1], 15
	s_add_i32 s15, s15, s72
	s_waitcnt lgkmcnt(0)
	v_mfma_f32_32x32x16_bf16 v[48:63], v[104:107], v[108:111], v[48:63]
	ds_read_b128 v[108:111], v91 offset:8704
	s_add_i32 s2, s2, s81
	s_add_i32 s14, s14, s82
	s_cmp_lt_i32 s15, s5
	s_cselect_b32 s99, 1, 0
	s_cbranch_scc0 .Lp1_nopf
	s_ashr_i32 s101, s15, 2
	s_abs_i32 s3, s101
	s_mul_hi_u32 s16, s3, s13
	s_mul_i32 s17, s16, s12
	s_ashr_i32 s100, s15, 31
	s_sub_i32 s3, s3, s17
	s_xor_b32 s100, s100, s11
	s_add_i32 s17, s16, 1
	s_sub_i32 s18, s3, s12
	s_cmp_ge_u32 s3, s12
	s_cselect_b32 s16, s17, s16
	s_cselect_b32 s3, s18, s3
	s_add_i32 s17, s16, 1
	s_cmp_ge_u32 s3, s12
	s_cselect_b32 s3, s17, s16
	s_xor_b32 s3, s3, s100
	s_sub_i32 s100, s3, s100
	s_mul_i32 s3, s100, s8
	s_sub_i32 s16, s101, s3
	s_ashr_i32 s17, s16, 31
	s_ashr_i32 s101, s100, 31
	s_lshl_b64 s[16:17], s[16:17], 20
	s_add_u32 s3, s6, s16
	s_addc_u32 s16, s7, s17
	s_lshl_b64 s[100:101], s[100:101], s10
	s_add_u32 s100, s3, s100
	s_addc_u32 s101, s16, s101
	s_and_b32 s3, s14, 0x180
	s_lshl_b32 s3, s3, 1
	s_add_u32 s100, s100, s3
	s_addc_u32 s101, s101, 0
	v_lshl_add_u64 v[136:137], s[100:101], 0, v[64:65]
	v_lshl_add_u64 v[138:139], v[136:137], 0, v[66:67]
	global_load_dwordx4 v[152:155], v[138:139], off offset:3072
	v_lshl_add_u64 v[140:141], v[136:137], 0, v[68:69]
	global_load_dwordx4 v[156:159], v[140:141], off offset:3072
	v_lshl_add_u64 v[144:145], v[136:137], 0, v[70:71]
	global_load_dwordx4 v[160:163], v[144:145], off offset:3072
	v_lshl_add_u64 v[148:149], v[136:137], 0, v[72:73]
	global_load_dwordx4 v[164:167], v[148:149], off offset:3072
	global_load_dwordx4 v[168:171], v[140:141], off offset:1024
	global_load_dwordx4 v[172:175], v[148:149], off offset:1024
	global_load_dwordx4 v[176:179], v[138:139], off offset:1024
	s_nop 0
	global_load_dwordx4 v[136:139], v[138:139], off offset:2048
	s_nop 0
	global_load_dwordx4 v[140:143], v[140:141], off offset:2048
	s_nop 0
	global_load_dwordx4 v[180:183], v[144:145], off offset:1024
	s_nop 0
	global_load_dwordx4 v[144:147], v[144:145], off offset:2048
	s_nop 0
	global_load_dwordx4 v[148:151], v[148:149], off offset:2048
.Lp1_nopf:
	v_mfma_f32_32x32x16_bf16 v[32:47], v[4:7], v[0:3], 0
	ds_read_b128 v[0:3], v90 offset:17408
	s_waitcnt lgkmcnt(1)
	v_mfma_f32_32x32x16_bf16 v[32:47], v[104:107], v[108:111], v[32:47]
	ds_read_b128 v[108:111], v91 offset:17408
	s_waitcnt lgkmcnt(1)
	v_mfma_f32_32x32x16_bf16 v[16:31], v[4:7], v[0:3], 0
	ds_read_b128 v[0:3], v90 offset:26112
	s_waitcnt lgkmcnt(1)
	v_mfma_f32_32x32x16_bf16 v[16:31], v[104:107], v[108:111], v[16:31]
	ds_read_b128 v[108:111], v91 offset:26112
	s_waitcnt lgkmcnt(1)
	v_mfma_f32_32x32x16_bf16 v[0:15], v[4:7], v[0:3], 0
	s_waitcnt lgkmcnt(0)
	v_mfma_f32_32x32x16_bf16 v[0:15], v[104:107], v[108:111], v[0:15]
	ds_read_b128 v[104:107], v89 offset:64
	v_add_u32_e32 v108, v81, v82
	ds_read_b128 v[108:111], v108
	s_waitcnt lgkmcnt(0)
	v_mfma_f32_32x32x16_bf16 v[48:63], v[104:107], v[108:111], v[48:63]
	ds_read_b128 v[108:111], v92 offset:8704
	s_waitcnt lgkmcnt(0)
	v_mfma_f32_32x32x16_bf16 v[32:47], v[104:107], v[108:111], v[32:47]
	ds_read_b128 v[108:111], v92 offset:17408
	s_waitcnt lgkmcnt(0)
	v_mfma_f32_32x32x16_bf16 v[16:31], v[104:107], v[108:111], v[16:31]
	ds_read_b128 v[108:111], v92 offset:26112
	s_waitcnt lgkmcnt(0)
	v_mfma_f32_32x32x16_bf16 v[0:15], v[104:107], v[108:111], v[0:15]
	ds_read_b128 v[104:107], v89 offset:96
	v_add_u32_e32 v108, v81, v83
	ds_read_b128 v[108:111], v108
	s_waitcnt lgkmcnt(0)
	v_mfma_f32_32x32x16_bf16 v[48:63], v[104:107], v[108:111], v[48:63]
	ds_read_b128 v[108:111], v93 offset:8704
	s_waitcnt lgkmcnt(0)
	v_mfma_f32_32x32x16_bf16 v[32:47], v[104:107], v[108:111], v[32:47]
	ds_read_b128 v[108:111], v93 offset:17408
	s_waitcnt lgkmcnt(0)
	v_mfma_f32_32x32x16_bf16 v[16:31], v[104:107], v[108:111], v[16:31]
	ds_read_b128 v[108:111], v93 offset:26112
	s_waitcnt lgkmcnt(0)
	v_mfma_f32_32x32x16_bf16 v[0:15], v[104:107], v[108:111], v[0:15]
	ds_read_b128 v[104:107], v89 offset:128
	v_add_u32_e32 v108, v81, v84
	ds_read_b128 v[108:111], v108
	s_waitcnt lgkmcnt(0)
	v_mfma_f32_32x32x16_bf16 v[48:63], v[104:107], v[108:111], v[48:63]
	ds_read_b128 v[108:111], v94 offset:8704
	s_waitcnt lgkmcnt(0)
	v_mfma_f32_32x32x16_bf16 v[32:47], v[104:107], v[108:111], v[32:47]
	ds_read_b128 v[108:111], v94 offset:17408
	s_waitcnt lgkmcnt(0)
	v_mfma_f32_32x32x16_bf16 v[16:31], v[104:107], v[108:111], v[16:31]
	ds_read_b128 v[108:111], v94 offset:26112
	s_waitcnt lgkmcnt(0)
	v_mfma_f32_32x32x16_bf16 v[0:15], v[104:107], v[108:111], v[0:15]
	ds_read_b128 v[104:107], v89 offset:160
	v_add_u32_e32 v108, v81, v85
	ds_read_b128 v[108:111], v108
	s_waitcnt lgkmcnt(0)
	v_mfma_f32_32x32x16_bf16 v[48:63], v[104:107], v[108:111], v[48:63]
	ds_read_b128 v[108:111], v95 offset:8704
	s_waitcnt lgkmcnt(0)
	v_mfma_f32_32x32x16_bf16 v[32:47], v[104:107], v[108:111], v[32:47]
	ds_read_b128 v[108:111], v95 offset:17408
	s_waitcnt lgkmcnt(0)
	v_mfma_f32_32x32x16_bf16 v[16:31], v[104:107], v[108:111], v[16:31]
	ds_read_b128 v[108:111], v95 offset:26112
	s_waitcnt lgkmcnt(0)
	v_mfma_f32_32x32x16_bf16 v[0:15], v[104:107], v[108:111], v[0:15]
	ds_read_b128 v[104:107], v89 offset:192
	v_add_u32_e32 v108, v81, v86
	ds_read_b128 v[108:111], v108
	s_waitcnt lgkmcnt(0)
; __device__ __forceinline__ unsigned pk2(float lo, float hi) { const f32x2_t v = {lo, hi}; return __builtin_bit_cast(unsigned, __builtin_convertvector(v, bf16x2_t)); }
; __device__ __forceinline__ void hgrn_pass1(const bf16* PROJ, bf16* ST, float* DEC, const float* lbl, int e, int L, LAS unsigned char* lds) {
;     ...
;         hgrn_ld_chunks(pb + 1536, tid, cv); hgrn_ld_chunks(pb + 512, tid, cz[0]); hgrn_ld_chunks(pb + 1024, tid, cz[1]);
;         hgrn_st_chunks(R0, tid, cv);
;         __syncthreads();
;         hgrn_build_vt(R0, VT, i, tq);
; #pragma unroll
;         for (int dir = 0; dir < 2; ++dir) {
;             __syncthreads();
;             hgrn_st_chunks(R0, tid, cz[dir]);
;             __syncthreads();
;     ...
;             bf16* Sg = ST + (size_t)(u * 2 + dir) * 16384;
; #pragma unroll
;             for (int jt = 0; jt < 4; ++jt)
; #pragma unroll
;                 for (int g = 0; g < 4; ++g) { v2u w; w.x = pk2(acc[jt][4 * g], acc[jt][4 * g + 1]); w.y = pk2(acc[jt][4 * g + 2], acc[jt][4 * g + 3]);
;                     *(v2u*)(Sg + (32 * jt + r32) * 128 + 32 * it + 8 * g + 4 * hh) = w; }
;         }
;         __syncthreads();
	v_mfma_f32_32x32x16_bf16 v[48:63], v[104:107], v[108:111], v[48:63]
	ds_read_b128 v[108:111], v96 offset:8704
	s_waitcnt lgkmcnt(0)
	v_mfma_f32_32x32x16_bf16 v[32:47], v[104:107], v[108:111], v[32:47]
	ds_read_b128 v[108:111], v96 offset:17408
	s_waitcnt lgkmcnt(0)
	v_mfma_f32_32x32x16_bf16 v[16:31], v[104:107], v[108:111], v[16:31]
	ds_read_b128 v[108:111], v96 offset:26112
	s_waitcnt lgkmcnt(0)
	v_mfma_f32_32x32x16_bf16 v[0:15], v[104:107], v[108:111], v[0:15]
	ds_read_b128 v[104:107], v89 offset:224
	v_add_u32_e32 v108, v81, v87
	ds_read_b128 v[108:111], v108
	s_waitcnt lgkmcnt(0)
	v_mfma_f32_32x32x16_bf16 v[48:63], v[104:107], v[108:111], v[48:63]
	ds_read_b128 v[108:111], v97 offset:8704
	s_waitcnt lgkmcnt(0)
	v_mfma_f32_32x32x16_bf16 v[32:47], v[104:107], v[108:111], v[32:47]
	ds_read_b128 v[108:111], v97 offset:17408
	s_nop 7
	v_cvt_pk_bf16_f32 v48, v48, v49
	v_cvt_pk_bf16_f32 v49, v50, v51
	s_waitcnt lgkmcnt(0)
	v_mfma_f32_32x32x16_bf16 v[16:31], v[104:107], v[108:111], v[16:31]
	ds_read_b128 v[108:111], v97 offset:26112
	v_cvt_pk_bf16_f32 v32, v32, v33
	v_cvt_pk_bf16_f32 v33, v34, v35
	s_waitcnt lgkmcnt(0)
	v_mfma_f32_32x32x16_bf16 v[0:15], v[104:107], v[108:111], v[0:15]
	v_lshl_add_u64 v[104:105], v[76:77], 0, s[0:1]
	v_add_co_u32_e64 v34, s[0:1], s38, v104
	s_nop 4
	v_cvt_pk_bf16_f32 v16, v16, v17
	v_addc_co_u32_e64 v35, s[0:1], 0, v105, s[0:1]
	v_cvt_pk_bf16_f32 v17, v18, v19
	v_add_co_u32_e64 v18, s[0:1], s20, v104
	s_nop 0
	v_cvt_pk_bf16_f32 v0, v0, v1
	v_addc_co_u32_e64 v19, s[0:1], 0, v105, s[0:1]
	v_cvt_pk_bf16_f32 v1, v2, v3
	v_add_co_u32_e64 v2, s[0:1], s21, v104
	global_store_dwordx2 v[104:105], v[48:49], off
	s_nop 0
	v_addc_co_u32_e64 v3, s[0:1], 0, v105, s[0:1]
	v_cvt_pk_bf16_f32 v48, v52, v53
	v_cvt_pk_bf16_f32 v49, v54, v55
	global_store_dwordx2 v[34:35], v[32:33], off
	v_cvt_pk_bf16_f32 v32, v36, v37
	v_cvt_pk_bf16_f32 v33, v38, v39
	global_store_dwordx2 v[18:19], v[16:17], off
	v_cvt_pk_bf16_f32 v16, v20, v21
	v_cvt_pk_bf16_f32 v17, v22, v23
	global_store_dwordx2 v[2:3], v[0:1], off
	v_cvt_pk_bf16_f32 v0, v4, v5
	v_cvt_pk_bf16_f32 v1, v6, v7
	global_store_dwordx2 v[104:105], v[48:49], off offset:16
	v_cvt_pk_bf16_f32 v48, v56, v57
	v_cvt_pk_bf16_f32 v49, v58, v59
	global_store_dwordx2 v[34:35], v[32:33], off offset:16
	v_cvt_pk_bf16_f32 v32, v40, v41
	v_cvt_pk_bf16_f32 v33, v42, v43
	global_store_dwordx2 v[18:19], v[16:17], off offset:16
	v_cvt_pk_bf16_f32 v16, v24, v25
	v_cvt_pk_bf16_f32 v17, v26, v27
	global_store_dwordx2 v[2:3], v[0:1], off offset:16
	v_cvt_pk_bf16_f32 v0, v8, v9
	v_cvt_pk_bf16_f32 v1, v10, v11
	global_store_dwordx2 v[104:105], v[48:49], off offset:32
	v_cvt_pk_bf16_f32 v48, v60, v61
	v_cvt_pk_bf16_f32 v49, v62, v63
	global_store_dwordx2 v[34:35], v[32:33], off offset:32
	v_cvt_pk_bf16_f32 v32, v44, v45
	v_cvt_pk_bf16_f32 v33, v46, v47
	global_store_dwordx2 v[18:19], v[16:17], off offset:32
	v_cvt_pk_bf16_f32 v16, v28, v29
	v_cvt_pk_bf16_f32 v17, v30, v31
	global_store_dwordx2 v[2:3], v[0:1], off offset:32
	v_cvt_pk_bf16_f32 v0, v12, v13
	v_cvt_pk_bf16_f32 v1, v14, v15
	global_store_dwordx2 v[104:105], v[48:49], off offset:48
	global_store_dwordx2 v[34:35], v[32:33], off offset:48
	global_store_dwordx2 v[18:19], v[16:17], off offset:48
	global_store_dwordx2 v[2:3], v[0:1], off offset:48
	s_barrier
	s_cmp_lg_u32 s99, 0
	s_cbranch_scc0 .LBB0_424
.LBB0_428:
	s_waitcnt vmcnt(16)
.Lp1_body:
	ds_write_b128 v98, v[152:155]
	ds_write_b128 v99, v[156:159]
	ds_write_b128 v100, v[160:163]
	ds_write_b128 v101, v[164:167]
	s_waitcnt lgkmcnt(0)
	s_barrier
	ds_read_u16 v16, v78
	ds_read_u16 v17, v78 offset:272
	ds_read_u16 v18, v78 offset:544
	ds_read_u16 v19, v78 offset:816
	ds_read_u16 v20, v78 offset:1088
	ds_read_u16 v21, v78 offset:1360
	ds_read_u16 v22, v78 offset:1632
	ds_read_u16 v23, v78 offset:1904
	ds_read_u16 v24, v78 offset:2176
	ds_read_u16 v25, v78 offset:2448
	ds_read_u16 v26, v78 offset:2720
	ds_read_u16 v27, v78 offset:2992
	ds_read_u16 v28, v78 offset:3264
	ds_read_u16 v29, v78 offset:3536
	ds_read_u16 v30, v78 offset:3808
	ds_read_u16 v31, v78 offset:4080
	ds_read_u16 v48, v78 offset:4352
	ds_read_u16 v49, v78 offset:4624
	ds_read_u16 v50, v78 offset:4896
	ds_read_u16 v51, v78 offset:5168
	ds_read_u16 v52, v78 offset:5440
	ds_read_u16 v53, v78 offset:5712
	ds_read_u16 v54, v78 offset:5984
	ds_read_u16 v55, v78 offset:6256
	ds_read_u16 v56, v78 offset:6528
	ds_read_u16 v57, v78 offset:6800
	ds_read_u16 v58, v78 offset:7072
	ds_read_u16 v59, v78 offset:7344
	ds_read_u16 v60, v78 offset:7616
	ds_read_u16 v61, v78 offset:7888
	ds_read_u16 v62, v78 offset:8160
	ds_read_u16 v63, v78 offset:8432
	s_waitcnt lgkmcnt(14)
	v_lshl_or_b32 v16, v17, 16, v16
	v_lshl_or_b32 v17, v19, 16, v18
	v_lshl_or_b32 v18, v21, 16, v20
	v_lshl_or_b32 v19, v23, 16, v22
	ds_write_b128 v88, v[16:19]
	v_lshl_or_b32 v16, v25, 16, v24
	v_lshl_or_b32 v17, v27, 16, v26
	v_lshl_or_b32 v18, v29, 16, v28
	v_lshl_or_b32 v19, v31, 16, v30
	ds_write_b128 v88, v[16:19] offset:16
	v_lshl_or_b32 v16, v49, 16, v48
	s_waitcnt lgkmcnt(14)
	v_lshl_or_b32 v17, v51, 16, v50
	s_waitcnt lgkmcnt(12)
	v_lshl_or_b32 v18, v53, 16, v52
	s_waitcnt lgkmcnt(10)
	v_lshl_or_b32 v19, v55, 16, v54
	ds_write_b128 v88, v[16:19] offset:32
	s_waitcnt lgkmcnt(9)
	v_lshl_or_b32 v16, v57, 16, v56
	s_waitcnt lgkmcnt(7)
	v_lshl_or_b32 v17, v59, 16, v58
	s_waitcnt lgkmcnt(5)
	v_lshl_or_b32 v18, v61, 16, v60
	s_waitcnt lgkmcnt(3)
	v_lshl_or_b32 v19, v63, 16, v62
	ds_write_b128 v88, v[16:19] offset:48
	s_waitcnt lgkmcnt(0)
	s_barrier
	ds_write_b128 v98, v[176:179]
	ds_write_b128 v99, v[168:171]
	ds_write_b128 v100, v[180:183]
	ds_write_b128 v101, v[172:175]
	s_waitcnt lgkmcnt(0)
	s_barrier
; #define LAS __attribute__((address_space(3)))
; __device__ __forceinline__ float ex2(float x) { return __builtin_amdgcn_exp2f(x); }
; __device__ __forceinline__ void hgrn_pass1(const bf16* PROJ, bf16* ST, float* DEC, const float* lbl, int e, int L, LAS unsigned char* lds) {
;     ...
;             float lf[32], kk[32]; float tot = 0.f;
; #pragma unroll
;             for (int uu = 0; uu < 32; ++uu) kk[uu] = __builtin_bit_cast(float, (unsigned)*(const LAS unsigned short*)(R0 + (32 * tq + uu) * LSTR + 2 * i));
;             __builtin_amdgcn_sched_barrier(0);
; #pragma unroll
;             for (int uu = 0; uu < 32; ++uu) { lf[uu] = __builtin_bit_cast(float, __builtin_bit_cast(unsigned, kk[uu]) << 16); kk[uu] = 1.0f - ex2(lf[uu]); tot += lf[uu]; }
;             TOT[(dir * 4 + tq) * 128 + i] = tot;
;             __syncthreads();
;             float off = 0.f, dtot = 0.f;
; #pragma unroll
;             for (int q = 0; q < 4; ++q) { const float tv = TOT[(dir * 4 + q) * 128 + i]; dtot += tv; if (dir == 0 ? (q > tq) : (q < tq)) off += tv; }
;             if (tq == 0) DEC[(size_t)(u * 2 + dir) * 128 + i] = ex2(dtot);
;             if (dir == 0) { float run = off;
; #pragma unroll
	ds_read_u16 v16, v78
	ds_read_u16 v17, v78 offset:272
	ds_read_u16 v18, v78 offset:544
	ds_read_u16 v19, v78 offset:816
	ds_read_u16 v20, v78 offset:1088
	ds_read_u16 v21, v78 offset:1360
	ds_read_u16 v27, v78 offset:1632
	ds_read_u16 v28, v78 offset:1904
	ds_read_u16 v29, v78 offset:2176
	ds_read_u16 v30, v78 offset:2448
	ds_read_u16 v31, v78 offset:2720
	ds_read_u16 v32, v78 offset:2992
	ds_read_u16 v33, v78 offset:3264
	ds_read_u16 v34, v78 offset:3536
	ds_read_u16 v35, v78 offset:3808
	ds_read_u16 v36, v78 offset:4080
	ds_read_u16 v37, v78 offset:4352
	ds_read_u16 v38, v78 offset:4624
	ds_read_u16 v39, v78 offset:4896
	ds_read_u16 v40, v78 offset:5168
	ds_read_u16 v41, v78 offset:5440
	ds_read_u16 v42, v78 offset:5712
	ds_read_u16 v43, v78 offset:5984
	ds_read_u16 v44, v78 offset:6256
	ds_read_u16 v45, v78 offset:6528
	ds_read_u16 v46, v78 offset:6800
	ds_read_u16 v47, v78 offset:7072
	ds_read_u16 v48, v78 offset:7344
	ds_read_u16 v49, v78 offset:7616
	ds_read_u16 v50, v78 offset:7888
	ds_read_u16 v51, v78 offset:8160
	ds_read_u16 v52, v78 offset:8432
	s_waitcnt lgkmcnt(14)
	v_lshlrev_b32_e32 v16, 16, v16
	v_add_f32_e32 v23, 0, v16
	v_lshlrev_b32_e32 v22, 16, v17
	v_add_f32_e32 v17, v23, v22
	v_lshlrev_b32_e32 v23, 16, v18
	v_add_f32_e32 v17, v17, v23
	v_lshlrev_b32_e32 v24, 16, v19
	v_add_f32_e32 v17, v17, v24
	v_lshlrev_b32_e32 v25, 16, v20
	v_add_f32_e32 v17, v17, v25
	v_lshlrev_b32_e32 v26, 16, v21
	v_add_f32_e32 v17, v17, v26
	v_lshlrev_b32_e32 v27, 16, v27
	v_add_f32_e32 v17, v17, v27
	v_lshlrev_b32_e32 v28, 16, v28
	v_add_f32_e32 v17, v17, v28
	v_lshlrev_b32_e32 v29, 16, v29
	v_add_f32_e32 v17, v17, v29
	v_lshlrev_b32_e32 v30, 16, v30
	v_add_f32_e32 v17, v17, v30
	v_lshlrev_b32_e32 v31, 16, v31
	v_add_f32_e32 v17, v17, v31
	v_lshlrev_b32_e32 v32, 16, v32
	v_add_f32_e32 v17, v17, v32
	v_lshlrev_b32_e32 v33, 16, v33
	v_add_f32_e32 v17, v17, v33
	v_lshlrev_b32_e32 v34, 16, v34
	v_add_f32_e32 v17, v17, v34
	v_lshlrev_b32_e32 v35, 16, v35
	v_add_f32_e32 v17, v17, v35
	v_lshlrev_b32_e32 v36, 16, v36
	v_add_f32_e32 v17, v17, v36
	v_lshlrev_b32_e32 v37, 16, v37
	v_add_f32_e32 v17, v17, v37
	v_lshlrev_b32_e32 v38, 16, v38
	v_add_f32_e32 v17, v17, v38
	s_waitcnt lgkmcnt(13)
	v_lshlrev_b32_e32 v39, 16, v39
	v_add_f32_e32 v17, v17, v39
	s_waitcnt lgkmcnt(12)
	v_lshlrev_b32_e32 v40, 16, v40
	v_add_f32_e32 v17, v17, v40
	s_waitcnt lgkmcnt(11)
	v_lshlrev_b32_e32 v41, 16, v41
	v_add_f32_e32 v17, v17, v41
	s_waitcnt lgkmcnt(10)
	v_lshlrev_b32_e32 v42, 16, v42
	v_add_f32_e32 v17, v17, v42
	s_waitcnt lgkmcnt(9)
	v_lshlrev_b32_e32 v43, 16, v43
	v_add_f32_e32 v17, v17, v43
	s_waitcnt lgkmcnt(8)
	v_lshlrev_b32_e32 v44, 16, v44
	v_add_f32_e32 v17, v17, v44
	s_waitcnt lgkmcnt(7)
	v_lshlrev_b32_e32 v45, 16, v45
	v_add_f32_e32 v17, v17, v45
	s_waitcnt lgkmcnt(6)
	v_lshlrev_b32_e32 v46, 16, v46
	v_add_f32_e32 v17, v17, v46
	s_waitcnt lgkmcnt(5)
	v_lshlrev_b32_e32 v47, 16, v47
	v_add_f32_e32 v17, v17, v47
	s_waitcnt lgkmcnt(4)
	v_lshlrev_b32_e32 v48, 16, v48
	v_add_f32_e32 v17, v17, v48
	s_waitcnt lgkmcnt(3)
	v_lshlrev_b32_e32 v49, 16, v49
	v_add_f32_e32 v17, v17, v49
	s_waitcnt lgkmcnt(2)
	v_lshlrev_b32_e32 v50, 16, v50
	v_add_f32_e32 v17, v17, v50
	s_waitcnt lgkmcnt(1)
	v_lshlrev_b32_e32 v51, 16, v51
	v_add_f32_e32 v17, v17, v51
	s_waitcnt lgkmcnt(0)
	v_lshlrev_b32_e32 v52, 16, v52
	v_add_f32_e32 v17, v17, v52
	ds_write_b32 v102, v17
	s_waitcnt lgkmcnt(0)
	s_barrier
	ds_read2st64_b32 v[18:19], v79 offset1:2
	ds_read2st64_b32 v[20:21], v79 offset0:4 offset1:6
	s_waitcnt lgkmcnt(1)
	v_add_f32_e32 v18, 0, v18
	s_and_saveexec_b64 s[0:1], vcc
	s_cbranch_execz .LBB0_430
	v_add_f32_e32 v17, v18, v19
	s_waitcnt lgkmcnt(0)
	v_add_f32_e32 v17, v17, v20
	v_add_f32_e32 v17, v17, v21
	v_exp_f32_e32 v17, v17
	s_ashr_i32 s3, s2, 31
	s_lshl_b64 s[16:17], s[2:3], 9
	v_lshl_add_u64 v[54:55], v[74:75], 0, s[16:17]
	global_store_dword v[54:55], v17, off
.LBB0_430:
	s_or_b64 exec, exec, s[0:1]
	v_cndmask_b32_e64 v18, 0, v18, s[42:43]
	v_add_f32_e32 v18, v19, v18
	v_cndmask_b32_e64 v18, 0, v18, s[44:45]
	s_waitcnt lgkmcnt(0)
	v_add_f32_e32 v18, v20, v18
	v_cndmask_b32_e64 v18, 0, v18, s[46:47]
	v_add_f32_e32 v18, v21, v18
	v_cndmask_b32_e64 v19, 0, v18, s[48:49]
	v_add_f32_e32 v20, v19, v52
	v_exp_f32_e32 v122, v51
	v_add_f32_e32 v51, v20, v51
	v_exp_f32_e32 v121, v50
	v_add_f32_e32 v50, v51, v50
	v_exp_f32_e32 v120, v49
	v_add_f32_e32 v49, v50, v49
	v_exp_f32_e32 v119, v48
	v_add_f32_e32 v48, v49, v48
	v_exp_f32_e32 v118, v47
	v_add_f32_e32 v47, v48, v47
	v_exp_f32_e32 v117, v46
	v_add_f32_e32 v46, v47, v46
	v_exp_f32_e32 v116, v45
	v_add_f32_e32 v45, v46, v45
	v_exp_f32_e32 v115, v44
	v_add_f32_e32 v44, v45, v44
	v_exp_f32_e32 v114, v43
	v_add_f32_e32 v43, v44, v43
	v_exp_f32_e32 v113, v42
	v_add_f32_e32 v42, v43, v42
	v_exp_f32_e32 v112, v41
	v_add_f32_e32 v41, v42, v41
	v_exp_f32_e32 v111, v40
	v_add_f32_e32 v40, v41, v40
	v_exp_f32_e32 v110, v39
	v_add_f32_e32 v39, v40, v39
	v_exp_f32_e32 v109, v38
	v_add_f32_e32 v38, v39, v38
	v_exp_f32_e32 v108, v37
	v_add_f32_e32 v37, v38, v37
	v_exp_f32_e32 v107, v36
	v_add_f32_e32 v36, v37, v36
	v_exp_f32_e32 v123, v52
	v_add_f32_e32 v52, v36, v35
	v_add_f32_e32 v53, v52, v34
	v_add_f32_e32 v124, v53, v33
	v_add_f32_e32 v125, v124, v32
	v_add_f32_e32 v126, v125, v31
	v_add_f32_e32 v127, v126, v30
	v_add_f32_e32 v128, v127, v29
	v_add_f32_e32 v129, v128, v28
	v_add_f32_e32 v130, v129, v27
	v_add_f32_e32 v131, v130, v26
	v_add_f32_e32 v132, v131, v25
	v_add_f32_e32 v133, v132, v24
	v_add_f32_e32 v134, v133, v23
	v_exp_f32_e32 v16, v16
	v_exp_f32_e32 v17, v22
	v_exp_f32_e32 v54, v23
	v_exp_f32_e32 v55, v24
	v_exp_f32_e32 v56, v25
; #define LAS __attribute__((address_space(3)))
; __device__ __forceinline__ unsigned pk2(float lo, float hi) { const f32x2_t v = {lo, hi}; return __builtin_bit_cast(unsigned, __builtin_convertvector(v, bf16x2_t)); }
; __device__ __forceinline__ float ex2(float x) { return __builtin_amdgcn_exp2f(x); }
; __device__ __forceinline__ void hgrn_pass1(const bf16* PROJ, bf16* ST, float* DEC, const float* lbl, int e, int L, LAS unsigned char* lds) {
;     ...
;             __syncthreads();
;             hgrn_st_chunks(R0, tid, cz[dir]);
;             __syncthreads();
;     ...
;             if (dir == 0) { float run = off;
; #pragma unroll
;     ...
;             else { float run = off;
; #pragma unroll
;                 for (int uu = 0; uu < 32; ++uu) { kk[uu] *= ex2(run); run += lf[uu]; } }
;             LAS unsigned char* KT = lds + dir * IMG;
; #pragma unroll
;             for (int m = 0; m < 4; ++m) { v4u w;
; #pragma unroll
;                 for (int x = 0; x < 4; ++x) w[x] = pk2(kk[8 * m + 2 * x], kk[8 * m + 2 * x + 1]);
;                 *(LAS v4u*)(KT + i * LSTR + (32 * tq + 8 * m) * 2) = w; }
	v_exp_f32_e32 v57, v26
	v_exp_f32_e32 v58, v27
	v_exp_f32_e32 v59, v28
	v_add_f32_e32 v18, v134, v22
	v_exp_f32_e32 v60, v29
	v_exp_f32_e32 v61, v30
	v_exp_f32_e32 v62, v31
	v_exp_f32_e32 v63, v32
	v_exp_f32_e32 v104, v33
	v_exp_f32_e32 v105, v34
	v_exp_f32_e32 v106, v35
	v_exp_f32_e32 v18, v18
	v_exp_f32_e32 v21, v19
	v_exp_f32_e32 v25, v49
	v_exp_f32_e32 v24, v48
	v_exp_f32_e32 v27, v47
	v_exp_f32_e32 v26, v46
	v_exp_f32_e32 v29, v45
	v_exp_f32_e32 v28, v44
	v_exp_f32_e32 v45, v128
	v_exp_f32_e32 v44, v129
	v_exp_f32_e32 v47, v130
	v_exp_f32_e32 v46, v131
	v_exp_f32_e32 v49, v132
	v_exp_f32_e32 v48, v133
	v_exp_f32_e32 v19, v134
	v_exp_f32_e32 v31, v43
	v_exp_f32_e32 v30, v42
	v_exp_f32_e32 v33, v41
	v_exp_f32_e32 v32, v40
	v_exp_f32_e32 v35, v39
	v_exp_f32_e32 v34, v38
	v_exp_f32_e32 v37, v37
	v_exp_f32_e32 v36, v36
	v_exp_f32_e32 v39, v52
	v_exp_f32_e32 v38, v53
	v_exp_f32_e32 v41, v124
	v_exp_f32_e32 v40, v125
	v_exp_f32_e32 v43, v126
	v_exp_f32_e32 v42, v127
	v_pk_add_f32 v[16:17], v[16:17], 1.0 op_sel_hi:[1,0] neg_lo:[1,0] neg_hi:[1,0]
	v_pk_add_f32 v[54:55], v[54:55], 1.0 op_sel_hi:[1,0] neg_lo:[1,0] neg_hi:[1,0]
	v_pk_add_f32 v[56:57], v[56:57], 1.0 op_sel_hi:[1,0] neg_lo:[1,0] neg_hi:[1,0]
	v_pk_add_f32 v[58:59], v[58:59], 1.0 op_sel_hi:[1,0] neg_lo:[1,0] neg_hi:[1,0]
	v_exp_f32_e32 v20, v20
	v_exp_f32_e32 v23, v51
	v_exp_f32_e32 v22, v50
	v_pk_add_f32 v[60:61], v[60:61], 1.0 op_sel_hi:[1,0] neg_lo:[1,0] neg_hi:[1,0]
	v_pk_add_f32 v[62:63], v[62:63], 1.0 op_sel_hi:[1,0] neg_lo:[1,0] neg_hi:[1,0]
	v_pk_add_f32 v[104:105], v[104:105], 1.0 op_sel_hi:[1,0] neg_lo:[1,0] neg_hi:[1,0]
	v_pk_add_f32 v[106:107], v[106:107], 1.0 op_sel_hi:[1,0] neg_lo:[1,0] neg_hi:[1,0]
	v_pk_mul_f32 v[44:45], v[58:59], v[44:45]
	v_pk_mul_f32 v[46:47], v[56:57], v[46:47]
	v_pk_mul_f32 v[48:49], v[54:55], v[48:49]
	v_pk_mul_f32 v[16:17], v[16:17], v[18:19]
	v_pk_add_f32 v[108:109], v[108:109], 1.0 op_sel_hi:[1,0] neg_lo:[1,0] neg_hi:[1,0]
	v_pk_add_f32 v[110:111], v[110:111], 1.0 op_sel_hi:[1,0] neg_lo:[1,0] neg_hi:[1,0]
	v_pk_add_f32 v[112:113], v[112:113], 1.0 op_sel_hi:[1,0] neg_lo:[1,0] neg_hi:[1,0]
	v_pk_add_f32 v[114:115], v[114:115], 1.0 op_sel_hi:[1,0] neg_lo:[1,0] neg_hi:[1,0]
	v_pk_mul_f32 v[36:37], v[106:107], v[36:37]
	v_pk_mul_f32 v[38:39], v[104:105], v[38:39]
	v_pk_mul_f32 v[40:41], v[62:63], v[40:41]
	v_pk_mul_f32 v[42:43], v[60:61], v[42:43]
	v_cvt_pk_bf16_f32 v16, v16, v17
	v_cvt_pk_bf16_f32 v17, v48, v49
	v_cvt_pk_bf16_f32 v18, v46, v47
	v_cvt_pk_bf16_f32 v19, v44, v45
	v_pk_add_f32 v[116:117], v[116:117], 1.0 op_sel_hi:[1,0] neg_lo:[1,0] neg_hi:[1,0]
	v_pk_add_f32 v[118:119], v[118:119], 1.0 op_sel_hi:[1,0] neg_lo:[1,0] neg_hi:[1,0]
	v_pk_add_f32 v[120:121], v[120:121], 1.0 op_sel_hi:[1,0] neg_lo:[1,0] neg_hi:[1,0]
	v_pk_add_f32 v[122:123], v[122:123], 1.0 op_sel_hi:[1,0] neg_lo:[1,0] neg_hi:[1,0]
	v_pk_mul_f32 v[28:29], v[114:115], v[28:29]
	v_pk_mul_f32 v[30:31], v[112:113], v[30:31]
	v_pk_mul_f32 v[32:33], v[110:111], v[32:33]
	v_pk_mul_f32 v[34:35], v[108:109], v[34:35]
	ds_write_b128 v103, v[16:19]
	v_cvt_pk_bf16_f32 v16, v42, v43
	v_cvt_pk_bf16_f32 v17, v40, v41
	v_cvt_pk_bf16_f32 v18, v38, v39
	v_cvt_pk_bf16_f32 v19, v36, v37
	v_pk_mul_f32 v[20:21], v[122:123], v[20:21]
	v_pk_mul_f32 v[22:23], v[120:121], v[22:23]
	v_pk_mul_f32 v[24:25], v[118:119], v[24:25]
	v_pk_mul_f32 v[26:27], v[116:117], v[26:27]
	ds_write_b128 v103, v[16:19] offset:16
	v_cvt_pk_bf16_f32 v16, v34, v35
	v_cvt_pk_bf16_f32 v17, v32, v33
	v_cvt_pk_bf16_f32 v18, v30, v31
	v_cvt_pk_bf16_f32 v19, v28, v29
	ds_write_b128 v103, v[16:19] offset:32
	v_cvt_pk_bf16_f32 v16, v26, v27
	v_cvt_pk_bf16_f32 v17, v24, v25
	v_cvt_pk_bf16_f32 v18, v22, v23
	v_cvt_pk_bf16_f32 v19, v20, v21
	ds_write_b128 v103, v[16:19] offset:48
	s_waitcnt lgkmcnt(0)
	s_barrier
	ds_write_b128 v98, v[136:139]
	ds_write_b128 v99, v[140:143]
	ds_write_b128 v100, v[144:147]
	ds_write_b128 v101, v[148:151]
	s_waitcnt lgkmcnt(0)
	s_barrier
; #define LAS __attribute__((address_space(3)))
; __device__ __forceinline__ float ex2(float x) { return __builtin_amdgcn_exp2f(x); }
; __device__ __forceinline__ void hgrn_pass1(const bf16* PROJ, bf16* ST, float* DEC, const float* lbl, int e, int L, LAS unsigned char* lds) {
;     ...
;             float lf[32], kk[32]; float tot = 0.f;
; #pragma unroll
;             for (int uu = 0; uu < 32; ++uu) kk[uu] = __builtin_bit_cast(float, (unsigned)*(const LAS unsigned short*)(R0 + (32 * tq + uu) * LSTR + 2 * i));
;             __builtin_amdgcn_sched_barrier(0);
; #pragma unroll
;             for (int uu = 0; uu < 32; ++uu) { lf[uu] = __builtin_bit_cast(float, __builtin_bit_cast(unsigned, kk[uu]) << 16); kk[uu] = 1.0f - ex2(lf[uu]); tot += lf[uu]; }
;             TOT[(dir * 4 + tq) * 128 + i] = tot;
;             __syncthreads();
;             float off = 0.f, dtot = 0.f;
; #pragma unroll
;             for (int q = 0; q < 4; ++q) { const float tv = TOT[(dir * 4 + q) * 128 + i]; dtot += tv; if (dir == 0 ? (q > tq) : (q < tq)) off += tv; }
;             if (tq == 0) DEC[(size_t)(u * 2 + dir) * 128 + i] = ex2(dtot);
	ds_read_u16 v0, v78
	ds_read_u16 v1, v78 offset:272
	ds_read_u16 v2, v78 offset:544
	ds_read_u16 v3, v78 offset:816
	ds_read_u16 v8, v78 offset:1088
	ds_read_u16 v9, v78 offset:1360
	ds_read_u16 v10, v78 offset:1632
	ds_read_u16 v11, v78 offset:1904
	ds_read_u16 v12, v78 offset:2176
	ds_read_u16 v13, v78 offset:2448
	ds_read_u16 v14, v78 offset:2720
	ds_read_u16 v15, v78 offset:2992
	ds_read_u16 v16, v78 offset:3264
	ds_read_u16 v17, v78 offset:3536
	ds_read_u16 v18, v78 offset:3808
	ds_read_u16 v19, v78 offset:4080
	ds_read_u16 v20, v78 offset:4352
	ds_read_u16 v21, v78 offset:4624
	ds_read_u16 v22, v78 offset:4896
	ds_read_u16 v23, v78 offset:5168
	ds_read_u16 v24, v78 offset:5440
	ds_read_u16 v25, v78 offset:5712
	ds_read_u16 v26, v78 offset:5984
	ds_read_u16 v27, v78 offset:6256
	ds_read_u16 v28, v78 offset:6528
	ds_read_u16 v29, v78 offset:6800
	ds_read_u16 v30, v78 offset:7072
	ds_read_u16 v31, v78 offset:7344
	ds_read_u16 v32, v78 offset:7616
	ds_read_u16 v33, v78 offset:7888
	ds_read_u16 v34, v78 offset:8160
	ds_read_u16 v35, v78 offset:8432
	s_waitcnt lgkmcnt(14)
	v_lshlrev_b32_e32 v4, 16, v0
	v_add_f32_e32 v0, 0, v4
	v_lshlrev_b32_e32 v5, 16, v1
	v_add_f32_e32 v0, v0, v5
	v_lshlrev_b32_e32 v6, 16, v2
	v_add_f32_e32 v0, v0, v6
	v_lshlrev_b32_e32 v7, 16, v3
	v_add_f32_e32 v0, v0, v7
	v_lshlrev_b32_e32 v8, 16, v8
	v_add_f32_e32 v0, v0, v8
	v_lshlrev_b32_e32 v9, 16, v9
	v_add_f32_e32 v0, v0, v9
	v_lshlrev_b32_e32 v10, 16, v10
	v_add_f32_e32 v0, v0, v10
	v_lshlrev_b32_e32 v11, 16, v11
	v_add_f32_e32 v0, v0, v11
	v_lshlrev_b32_e32 v12, 16, v12
	v_add_f32_e32 v0, v0, v12
	v_lshlrev_b32_e32 v13, 16, v13
	v_add_f32_e32 v0, v0, v13
	v_lshlrev_b32_e32 v14, 16, v14
	v_add_f32_e32 v0, v0, v14
	v_lshlrev_b32_e32 v15, 16, v15
	v_add_f32_e32 v0, v0, v15
	v_lshlrev_b32_e32 v16, 16, v16
	v_add_f32_e32 v0, v0, v16
	v_lshlrev_b32_e32 v17, 16, v17
	v_add_f32_e32 v0, v0, v17
	v_lshlrev_b32_e32 v18, 16, v18
	v_add_f32_e32 v0, v0, v18
	v_lshlrev_b32_e32 v19, 16, v19
	v_add_f32_e32 v0, v0, v19
	v_lshlrev_b32_e32 v20, 16, v20
	v_add_f32_e32 v0, v0, v20
	v_lshlrev_b32_e32 v21, 16, v21
	v_add_f32_e32 v0, v0, v21
	s_waitcnt lgkmcnt(13)
	v_lshlrev_b32_e32 v22, 16, v22
	v_add_f32_e32 v0, v0, v22
	s_waitcnt lgkmcnt(12)
	v_lshlrev_b32_e32 v23, 16, v23
	v_add_f32_e32 v0, v0, v23
	s_waitcnt lgkmcnt(11)
	v_lshlrev_b32_e32 v24, 16, v24
	v_add_f32_e32 v0, v0, v24
	s_waitcnt lgkmcnt(10)
	v_lshlrev_b32_e32 v25, 16, v25
	v_add_f32_e32 v0, v0, v25
	s_waitcnt lgkmcnt(9)
	v_lshlrev_b32_e32 v26, 16, v26
	v_add_f32_e32 v0, v0, v26
	s_waitcnt lgkmcnt(8)
	v_lshlrev_b32_e32 v27, 16, v27
	v_add_f32_e32 v0, v0, v27
	s_waitcnt lgkmcnt(7)
	v_lshlrev_b32_e32 v28, 16, v28
	v_add_f32_e32 v0, v0, v28
	s_waitcnt lgkmcnt(6)
	v_lshlrev_b32_e32 v29, 16, v29
	v_add_f32_e32 v0, v0, v29
	s_waitcnt lgkmcnt(5)
	v_lshlrev_b32_e32 v30, 16, v30
	v_add_f32_e32 v0, v0, v30
	s_waitcnt lgkmcnt(4)
	v_lshlrev_b32_e32 v31, 16, v31
	v_add_f32_e32 v0, v0, v31
	s_waitcnt lgkmcnt(3)
	v_lshlrev_b32_e32 v32, 16, v32
	v_add_f32_e32 v0, v0, v32
	s_waitcnt lgkmcnt(2)
	v_lshlrev_b32_e32 v33, 16, v33
	v_add_f32_e32 v0, v0, v33
	s_waitcnt lgkmcnt(1)
	v_lshlrev_b32_e32 v34, 16, v34
	v_add_f32_e32 v0, v0, v34
	s_waitcnt lgkmcnt(0)
	v_lshlrev_b32_e32 v35, 16, v35
	v_add_f32_e32 v0, v0, v35
	ds_write_b32 v102, v0 offset:2048
	s_waitcnt lgkmcnt(0)
	s_barrier
	ds_read2st64_b32 v[0:1], v79 offset0:8 offset1:10
	ds_read2st64_b32 v[2:3], v79 offset0:12 offset1:14
	s_waitcnt lgkmcnt(1)
	v_add_f32_e32 v0, 0, v0
	s_and_saveexec_b64 s[0:1], vcc
	s_cbranch_execz .LBB0_427
	v_add_f32_e32 v36, v0, v1
	s_waitcnt lgkmcnt(0)
	v_add_f32_e32 v36, v36, v2
	v_add_f32_e32 v36, v36, v3
	s_add_i32 s16, s2, 1
	v_exp_f32_e32 v38, v36
	s_ashr_i32 s17, s16, 31
	s_lshl_b64 s[16:17], s[16:17], 9
	v_lshl_add_u64 v[36:37], v[74:75], 0, s[16:17]
	global_store_dword v[36:37], v38, off
	s_branch .LBB0_427
